# non-temporal (nt) hint on the 64 epilogue stores of the third GEMM instance only (k-loop .LBB0_176); other GEMM epilogues unchanged
# baseline (speedup 1.0000x reference)
; __device__ __forceinline__ void lds_barrier() { asm volatile("s_waitcnt lgkmcnt(0)\n\ts_barrier" ::: "memory"); }
; template <int EPI>
; __device__ void gemm_phase(const u16* __restrict__ A, const u16* __restrict__ Bt, void* __restrict__ Cv,
;                            int N, int K, int ldc, unsigned char* ldsraw, int G) {
;     ...
;     for (int kt = 0; kt < nk; ++kt) {
;       asm volatile("s_waitcnt vmcnt(6)" ::: "memory");
;       lds_barrier();
;       const int st2 = (st >= 1) ? st - 1 : 2;
;       GLDS(st2, kt + 2);
;       const u16* Asx = As + st * STG;
;       const u16* Bsx = Asx + GBM * GLD;
; #pragma unroll
;       for (int ks = 0; ks < 2; ++ks) {
;         const int fsw = ((ks * 4 + g4) ^ fx) * 8;
;         bf16x8 bfr[4];
; #pragma unroll
;         for (int jx = 0; jx < 4; ++jx) bfr[jx] = *(const bf16x8*)(Bsx + (wn * 64 + jx * 16 + l15) * GLD + fsw);
; #pragma unroll
;         for (int ix = 0; ix < 4; ++ix) {
;           const bf16x8 af = *(const bf16x8*)(Asx + (wm * 64 + ix * 16 + l15) * GLD + fsw);
; #pragma unroll
;           for (int jx = 0; jx < 4; ++jx)
;             acc[ix][jx] = __builtin_amdgcn_mfma_f32_16x16x32_bf16(af, bfr[jx], acc[ix][jx], 0, 0, 0);
;         }
;       }
;       st = (st == 2) ? 0 : st + 1;
;     }
;     __builtin_amdgcn_s_setprio(0);
;     asm volatile("s_waitcnt vmcnt(0)" ::: "memory");
;     lds_barrier();
;     ...
; #pragma unroll
;     for (int i = 0; i < 4; ++i) {
; #pragma unroll
;       for (int r = 0; r < 4; ++r) {
;         const int m = m0 + wm * 64 + i * 16 + g4 * 4 + r;
;         const int nb = n0 + wn * 64 + l15;
;         if (EPI == EPI_F32) {
;           float* cp = (float*)Cv + (size_t)m * ldc + nb;
; #pragma unroll
;           for (int j = 0; j < 4; ++j) if (nb + j * 16 < N) cp[j * 16] = acc[i][j][r];
;         } else {
;           u16* cp = (u16*)Cv + (size_t)m * ldc + nb;
; #pragma unroll
;           for (int j = 0; j < 4; ++j) {
;             float v = acc[i][j][r];
;             if (EPI == EPI_RELU2) { v = fmaxf(v, 0.f); v = v * v; }
;             if (nb + j * 16 < N) cp[j * 16] = f2bf(v);
.LBB0_176:
	s_waitcnt vmcnt(6)
	s_waitcnt lgkmcnt(0)
	s_barrier
	s_mov_b32 s15, m0
	ds_read_b128 v[110:113], v109
	ds_read_b128 v[114:117], v251 offset:32768
	ds_read_b128 v[118:121], v251 offset:34816
	ds_read_b128 v[122:125], v109 offset:2048
	ds_read_b128 v[126:129], v251 offset:36864
	ds_read_b128 v[130:133], v251 offset:38912
	s_waitcnt lgkmcnt(4)
	v_mfma_f32_16x16x32_bf16 v[64:67], v[110:113], v[114:117], v[64:67]
	s_waitcnt lgkmcnt(3)
	v_mfma_f32_16x16x32_bf16 v[60:63], v[110:113], v[118:121], v[60:63]
	s_waitcnt lgkmcnt(1)
	v_mfma_f32_16x16x32_bf16 v[56:59], v[110:113], v[126:129], v[56:59]
	s_waitcnt lgkmcnt(0)
	s_mov_b32 m0, s8
	v_mfma_f32_16x16x32_bf16 v[52:55], v[110:113], v[130:133], v[52:55]
	global_load_lds_dwordx4 v[236:237], off
	v_mfma_f32_16x16x32_bf16 v[48:51], v[122:125], v[114:117], v[48:51]
	v_mfma_f32_16x16x32_bf16 v[44:47], v[122:125], v[118:121], v[44:47]
	v_mfma_f32_16x16x32_bf16 v[40:43], v[122:125], v[126:129], v[40:43]
	v_mfma_f32_16x16x32_bf16 v[36:39], v[122:125], v[130:133], v[36:39]
	ds_read_b128 v[110:113], v109 offset:4096
	ds_read_b128 v[122:125], v109 offset:6144
	v_lshl_add_u32 v109, v108, 1, s7
	v_add3_u32 v134, v109, v105, v106
	v_add3_u32 v109, v109, v107, v106
	s_waitcnt lgkmcnt(1)
	s_mov_b32 m0, s9
	v_mfma_f32_16x16x32_bf16 v[32:35], v[110:113], v[114:117], v[32:35]
	global_load_lds_dwordx4 v[238:239], off
	s_add_i32 s7, s5, 1
	s_cmp_lg_u32 s5, 2
	s_cselect_b32 s5, s7, 0
	v_mfma_f32_16x16x32_bf16 v[28:31], v[110:113], v[118:121], v[28:31]
	s_add_i32 s6, s6, 1
	v_mfma_f32_16x16x32_bf16 v[24:27], v[110:113], v[126:129], v[24:27]
	v_mfma_f32_16x16x32_bf16 v[20:23], v[110:113], v[130:133], v[20:23]
	ds_read_b128 v[110:113], v109
	s_waitcnt lgkmcnt(1)
	v_mfma_f32_16x16x32_bf16 v[16:19], v[122:125], v[114:117], v[16:19]
	s_mov_b32 m0, s11
	v_mfma_f32_16x16x32_bf16 v[12:15], v[122:125], v[118:121], v[12:15]
	global_load_lds_dwordx4 v[240:241], off
	v_mfma_f32_16x16x32_bf16 v[8:11], v[122:125], v[126:129], v[8:11]
	v_mfma_f32_16x16x32_bf16 v[2:5], v[122:125], v[130:133], v[2:5]
	ds_read_b128 v[114:117], v134 offset:32768
	ds_read_b128 v[118:121], v134 offset:34816
	ds_read_b128 v[122:125], v109 offset:2048
	ds_read_b128 v[126:129], v134 offset:36864
	ds_read_b128 v[130:133], v134 offset:38912
	s_waitcnt lgkmcnt(4)
	v_mfma_f32_16x16x32_bf16 v[64:67], v[110:113], v[114:117], v[64:67]
	s_waitcnt lgkmcnt(3)
	v_mfma_f32_16x16x32_bf16 v[60:63], v[110:113], v[118:121], v[60:63]
	s_waitcnt lgkmcnt(1)
	s_mov_b32 m0, s12
	v_mfma_f32_16x16x32_bf16 v[56:59], v[110:113], v[126:129], v[56:59]
	global_load_lds_dwordx4 v[242:243], off
	s_waitcnt lgkmcnt(0)
	v_mfma_f32_16x16x32_bf16 v[52:55], v[110:113], v[130:133], v[52:55]
	v_mfma_f32_16x16x32_bf16 v[48:51], v[122:125], v[114:117], v[48:51]
	v_mfma_f32_16x16x32_bf16 v[44:47], v[122:125], v[118:121], v[44:47]
	v_mfma_f32_16x16x32_bf16 v[40:43], v[122:125], v[126:129], v[40:43]
	s_mov_b32 m0, s13
	v_mfma_f32_16x16x32_bf16 v[36:39], v[122:125], v[130:133], v[36:39]
	global_load_lds_dwordx4 v[244:245], off
	ds_read_b128 v[110:113], v109 offset:4096
	ds_read_b128 v[122:125], v109 offset:6144
	s_waitcnt lgkmcnt(1)
	v_mfma_f32_16x16x32_bf16 v[32:35], v[110:113], v[114:117], v[32:35]
	v_mfma_f32_16x16x32_bf16 v[28:31], v[110:113], v[118:121], v[28:31]
	v_mfma_f32_16x16x32_bf16 v[24:27], v[110:113], v[126:129], v[24:27]
	v_mfma_f32_16x16x32_bf16 v[20:23], v[110:113], v[130:133], v[20:23]
	s_waitcnt lgkmcnt(0)
	s_mov_b32 m0, s14
	v_mfma_f32_16x16x32_bf16 v[16:19], v[122:125], v[114:117], v[16:19]
	global_load_lds_dwordx4 v[246:247], off
	s_mov_b32 m0, s15
	s_mul_i32 s8, s5, 0xc000
	s_min_u32 s7, s6, 13
	s_add_i32 s9, s8, 0xffff4000
	s_cmp_gt_i32 s5, 0
	s_cselect_b32 s9, s9, 0x18000
	s_lshl_b32 s98, s7, 7
	s_add_i32 s98, s98, 0x100
	s_add_i32 s7, s8, 0x100
	s_add_i32 s8, s9, s4
	s_add_i32 s9, s8, 0x2000
	s_add_i32 s11, s8, 0x4000
	s_add_i32 s12, s8, 0x6000
	s_add_i32 s13, s8, 0x8000
	s_add_i32 s14, s8, 0xa000
	v_mfma_f32_16x16x32_bf16 v[12:15], v[122:125], v[118:121], v[12:15]
	v_lshl_add_u64 v[236:237], v[76:77], 0, s[98:99]
	v_lshl_add_u64 v[238:239], v[80:81], 0, s[98:99]
	v_lshl_add_u64 v[240:241], v[82:83], 0, s[98:99]
	v_mfma_f32_16x16x32_bf16 v[8:11], v[122:125], v[126:129], v[8:11]
	v_lshl_add_u64 v[242:243], v[84:85], 0, s[98:99]
	v_lshl_add_u64 v[244:245], v[78:79], 0, s[98:99]
	v_lshl_add_u64 v[246:247], v[86:87], 0, s[98:99]
	v_mfma_f32_16x16x32_bf16 v[2:5], v[122:125], v[130:133], v[2:5]
	v_lshl_add_u32 v109, v104, 1, s7
	v_add3_u32 v251, v109, v105, v106
	v_add3_u32 v109, v109, v107, v106
	s_cmp_eq_u32 s6, 16
	s_cbranch_scc0 .LBB0_176
	s_setprio 0
	s_waitcnt vmcnt(0)
	v_add_u32_e32 v78, s0, v0
	v_or_b32_e32 v82, s1, v75
	s_waitcnt lgkmcnt(0)
	s_barrier
	v_ashrrev_i32_e32 v83, 31, v82
	v_ashrrev_i32_e32 v79, 31, v78
	v_lshl_add_u64 v[76:77], v[82:83], 1, s[76:77]
	v_lshlrev_b64 v[80:81], 11, v[78:79]
	s_movk_i32 s0, 0x400
	v_lshl_add_u64 v[80:81], v[76:77], 0, v[80:81]
	v_cmp_gt_i32_e32 vcc, s0, v82
	s_and_saveexec_b64 s[0:1], vcc
	s_cbranch_execz .LBB0_179
	v_bfe_u32 v79, v64, 16, 1
	v_add3_u32 v64, v64, v79, s96
	global_store_short_d16_hi v[80:81], v64, off nt
.LBB0_179:
	s_or_b64 exec, exec, s[0:1]
	v_or_b32_e32 v64, 16, v82
	s_movk_i32 s0, 0x400
	v_cmp_gt_i32_e64 s[4:5], s0, v64
	s_and_saveexec_b64 s[0:1], s[4:5]
	s_cbranch_execz .LBB0_181
	v_bfe_u32 v64, v60, 16, 1
	v_add3_u32 v60, v60, v64, s96
	global_store_short_d16_hi v[80:81], v60, off offset:32 nt
.LBB0_181:
	s_or_b64 exec, exec, s[0:1]
	v_or_b32_e32 v60, 32, v82
	s_movk_i32 s0, 0x400
	v_cmp_gt_i32_e64 s[6:7], s0, v60
	s_and_saveexec_b64 s[0:1], s[6:7]
	s_cbranch_execz .LBB0_183
	v_bfe_u32 v60, v56, 16, 1
	v_add3_u32 v56, v56, v60, s96
	global_store_short_d16_hi v[80:81], v56, off offset:64 nt
.LBB0_183:
	s_or_b64 exec, exec, s[0:1]
	v_or_b32_e32 v56, 48, v82
	s_movk_i32 s0, 0x400
	v_cmp_gt_i32_e64 s[8:9], s0, v56
	s_and_saveexec_b64 s[0:1], s[8:9]
	s_cbranch_execz .LBB0_185
	v_bfe_u32 v56, v52, 16, 1
	v_add3_u32 v52, v52, v56, s96
	global_store_short_d16_hi v[80:81], v52, off offset:96 nt

; template <int EPI>
; __device__ void gemm_phase(const u16* __restrict__ A, const u16* __restrict__ Bt, void* __restrict__ Cv,
;                            int N, int K, int ldc, unsigned char* ldsraw, int G) {
;     ...
;           for (int j = 0; j < 4; ++j) if (nb + j * 16 < N) cp[j * 16] = acc[i][j][r];
;         } else {
;           u16* cp = (u16*)Cv + (size_t)m * ldc + nb;
; #pragma unroll
;           for (int j = 0; j < 4; ++j) {
;             float v = acc[i][j][r];
;             if (EPI == EPI_RELU2) { v = fmaxf(v, 0.f); v = v * v; }
;             if (nb + j * 16 < N) cp[j * 16] = f2bf(v);
.LBB0_189:
	v_bfe_u32 v52, v53, 16, 1
	v_add3_u32 v52, v53, v52, s96
	global_store_short_d16_hi v[80:81], v52, off offset:96 nt

; template <int EPI>
; __device__ void gemm_phase(const u16* __restrict__ A, const u16* __restrict__ Bt, void* __restrict__ Cv,
;                            int N, int K, int ldc, unsigned char* ldsraw, int G) {
;     ...
;           for (int j = 0; j < 4; ++j) if (nb + j * 16 < N) cp[j * 16] = acc[i][j][r];
;         } else {
;           u16* cp = (u16*)Cv + (size_t)m * ldc + nb;
; #pragma unroll
;           for (int j = 0; j < 4; ++j) {
;             float v = acc[i][j][r];
;             if (EPI == EPI_RELU2) { v = fmaxf(v, 0.f); v = v * v; }
;             if (nb + j * 16 < N) cp[j * 16] = f2bf(v);
.LBB0_194:
	v_bfe_u32 v56, v54, 16, 1
	v_add3_u32 v54, v54, v56, s96
	global_store_short_d16_hi v[52:53], v54, off offset:96 nt

; template <int EPI>
; __device__ void gemm_phase(const u16* __restrict__ A, const u16* __restrict__ Bt, void* __restrict__ Cv,
;                            int N, int K, int ldc, unsigned char* ldsraw, int G) {
;     ...
;           for (int j = 0; j < 4; ++j) if (nb + j * 16 < N) cp[j * 16] = acc[i][j][r];
;         } else {
;           u16* cp = (u16*)Cv + (size_t)m * ldc + nb;
; #pragma unroll
;           for (int j = 0; j < 4; ++j) {
;             float v = acc[i][j][r];
;             if (EPI == EPI_RELU2) { v = fmaxf(v, 0.f); v = v * v; }
;             if (nb + j * 16 < N) cp[j * 16] = f2bf(v);
.LBB0_199:
	v_bfe_u32 v54, v55, 16, 1
	v_add3_u32 v54, v55, v54, s96
	global_store_short_d16_hi v[52:53], v54, off offset:96 nt

; template <int EPI>
; __device__ void gemm_phase(const u16* __restrict__ A, const u16* __restrict__ Bt, void* __restrict__ Cv,
;                            int N, int K, int ldc, unsigned char* ldsraw, int G) {
;     ...
;           for (int j = 0; j < 4; ++j) if (nb + j * 16 < N) cp[j * 16] = acc[i][j][r];
;         } else {
;           u16* cp = (u16*)Cv + (size_t)m * ldc + nb;
; #pragma unroll
;           for (int j = 0; j < 4; ++j) {
;             float v = acc[i][j][r];
;             if (EPI == EPI_RELU2) { v = fmaxf(v, 0.f); v = v * v; }
;             if (nb + j * 16 < N) cp[j * 16] = f2bf(v);
.LBB0_204:
	v_bfe_u32 v40, v36, 16, 1
	v_add3_u32 v36, v36, v40, s96
	global_store_short_d16_hi v[52:53], v36, off offset:96 nt

; template <int EPI>
; __device__ void gemm_phase(const u16* __restrict__ A, const u16* __restrict__ Bt, void* __restrict__ Cv,
;                            int N, int K, int ldc, unsigned char* ldsraw, int G) {
;     ...
;           for (int j = 0; j < 4; ++j) if (nb + j * 16 < N) cp[j * 16] = acc[i][j][r];
;         } else {
;           u16* cp = (u16*)Cv + (size_t)m * ldc + nb;
; #pragma unroll
;           for (int j = 0; j < 4; ++j) {
;             float v = acc[i][j][r];
;             if (EPI == EPI_RELU2) { v = fmaxf(v, 0.f); v = v * v; }
;             if (nb + j * 16 < N) cp[j * 16] = f2bf(v);
.LBB0_209:
	v_bfe_u32 v36, v37, 16, 1
	v_add3_u32 v36, v37, v36, s96
	global_store_short_d16_hi v[52:53], v36, off offset:96 nt

; template <int EPI>
; __device__ void gemm_phase(const u16* __restrict__ A, const u16* __restrict__ Bt, void* __restrict__ Cv,
;                            int N, int K, int ldc, unsigned char* ldsraw, int G) {
;     ...
;           for (int j = 0; j < 4; ++j) if (nb + j * 16 < N) cp[j * 16] = acc[i][j][r];
;         } else {
;           u16* cp = (u16*)Cv + (size_t)m * ldc + nb;
; #pragma unroll
;           for (int j = 0; j < 4; ++j) {
;             float v = acc[i][j][r];
;             if (EPI == EPI_RELU2) { v = fmaxf(v, 0.f); v = v * v; }
;             if (nb + j * 16 < N) cp[j * 16] = f2bf(v);
.LBB0_214:
	v_bfe_u32 v40, v38, 16, 1
	v_add3_u32 v38, v38, v40, s96
	global_store_short_d16_hi v[36:37], v38, off offset:96 nt

; template <int EPI>
; __device__ void gemm_phase(const u16* __restrict__ A, const u16* __restrict__ Bt, void* __restrict__ Cv,
;                            int N, int K, int ldc, unsigned char* ldsraw, int G) {
;     ...
;           for (int j = 0; j < 4; ++j) if (nb + j * 16 < N) cp[j * 16] = acc[i][j][r];
;         } else {
;           u16* cp = (u16*)Cv + (size_t)m * ldc + nb;
; #pragma unroll
;           for (int j = 0; j < 4; ++j) {
;             float v = acc[i][j][r];
;             if (EPI == EPI_RELU2) { v = fmaxf(v, 0.f); v = v * v; }
;             if (nb + j * 16 < N) cp[j * 16] = f2bf(v);
.LBB0_219:
	v_bfe_u32 v38, v39, 16, 1
	v_add3_u32 v38, v39, v38, s96
	global_store_short_d16_hi v[36:37], v38, off offset:96 nt

; template <int EPI>
; __device__ void gemm_phase(const u16* __restrict__ A, const u16* __restrict__ Bt, void* __restrict__ Cv,
;                            int N, int K, int ldc, unsigned char* ldsraw, int G) {
;     ...
;           for (int j = 0; j < 4; ++j) if (nb + j * 16 < N) cp[j * 16] = acc[i][j][r];
;         } else {
;           u16* cp = (u16*)Cv + (size_t)m * ldc + nb;
; #pragma unroll
;           for (int j = 0; j < 4; ++j) {
;             float v = acc[i][j][r];
;             if (EPI == EPI_RELU2) { v = fmaxf(v, 0.f); v = v * v; }
;             if (nb + j * 16 < N) cp[j * 16] = f2bf(v);
.LBB0_224:
	v_bfe_u32 v24, v20, 16, 1
	v_add3_u32 v20, v20, v24, s96
	global_store_short_d16_hi v[36:37], v20, off offset:96 nt

; template <int EPI>
; __device__ void gemm_phase(const u16* __restrict__ A, const u16* __restrict__ Bt, void* __restrict__ Cv,
;                            int N, int K, int ldc, unsigned char* ldsraw, int G) {
;     ...
;           for (int j = 0; j < 4; ++j) if (nb + j * 16 < N) cp[j * 16] = acc[i][j][r];
;         } else {
;           u16* cp = (u16*)Cv + (size_t)m * ldc + nb;
; #pragma unroll
;           for (int j = 0; j < 4; ++j) {
;             float v = acc[i][j][r];
;             if (EPI == EPI_RELU2) { v = fmaxf(v, 0.f); v = v * v; }
;             if (nb + j * 16 < N) cp[j * 16] = f2bf(v);
.LBB0_229:
	v_bfe_u32 v20, v21, 16, 1
	v_add3_u32 v20, v21, v20, s96
	global_store_short_d16_hi v[36:37], v20, off offset:96 nt

; template <int EPI>
; __device__ void gemm_phase(const u16* __restrict__ A, const u16* __restrict__ Bt, void* __restrict__ Cv,
;                            int N, int K, int ldc, unsigned char* ldsraw, int G) {
;     ...
;           for (int j = 0; j < 4; ++j) if (nb + j * 16 < N) cp[j * 16] = acc[i][j][r];
;         } else {
;           u16* cp = (u16*)Cv + (size_t)m * ldc + nb;
; #pragma unroll
;           for (int j = 0; j < 4; ++j) {
;             float v = acc[i][j][r];
;             if (EPI == EPI_RELU2) { v = fmaxf(v, 0.f); v = v * v; }
;             if (nb + j * 16 < N) cp[j * 16] = f2bf(v);
.LBB0_234:
	v_bfe_u32 v24, v22, 16, 1
	v_add3_u32 v22, v22, v24, s96
	global_store_short_d16_hi v[20:21], v22, off offset:96 nt

; template <int EPI>
; __device__ void gemm_phase(const u16* __restrict__ A, const u16* __restrict__ Bt, void* __restrict__ Cv,
;                            int N, int K, int ldc, unsigned char* ldsraw, int G) {
;     ...
;           for (int j = 0; j < 4; ++j) if (nb + j * 16 < N) cp[j * 16] = acc[i][j][r];
;         } else {
;           u16* cp = (u16*)Cv + (size_t)m * ldc + nb;
; #pragma unroll
;           for (int j = 0; j < 4; ++j) {
;             float v = acc[i][j][r];
;             if (EPI == EPI_RELU2) { v = fmaxf(v, 0.f); v = v * v; }
;             if (nb + j * 16 < N) cp[j * 16] = f2bf(v);
.LBB0_239:
	v_bfe_u32 v22, v23, 16, 1
	v_add3_u32 v22, v23, v22, s96
	global_store_short_d16_hi v[20:21], v22, off offset:96 nt

; template <int EPI>
; __device__ void gemm_phase(const u16* __restrict__ A, const u16* __restrict__ Bt, void* __restrict__ Cv,
;                            int N, int K, int ldc, unsigned char* ldsraw, int G) {
;     ...
;           for (int j = 0; j < 4; ++j) if (nb + j * 16 < N) cp[j * 16] = acc[i][j][r];
;         } else {
;           u16* cp = (u16*)Cv + (size_t)m * ldc + nb;
; #pragma unroll
;           for (int j = 0; j < 4; ++j) {
;             float v = acc[i][j][r];
;             if (EPI == EPI_RELU2) { v = fmaxf(v, 0.f); v = v * v; }
;             if (nb + j * 16 < N) cp[j * 16] = f2bf(v);
.LBB0_244:
	v_bfe_u32 v8, v2, 16, 1
	v_add3_u32 v2, v2, v8, s96
	global_store_short_d16_hi v[20:21], v2, off offset:96 nt

; template <int EPI>
; __device__ void gemm_phase(const u16* __restrict__ A, const u16* __restrict__ Bt, void* __restrict__ Cv,
;                            int N, int K, int ldc, unsigned char* ldsraw, int G) {
;     ...
;           for (int j = 0; j < 4; ++j) if (nb + j * 16 < N) cp[j * 16] = acc[i][j][r];
;         } else {
;           u16* cp = (u16*)Cv + (size_t)m * ldc + nb;
; #pragma unroll
;           for (int j = 0; j < 4; ++j) {
;             float v = acc[i][j][r];
;             if (EPI == EPI_RELU2) { v = fmaxf(v, 0.f); v = v * v; }
;             if (nb + j * 16 < N) cp[j * 16] = f2bf(v);
.LBB0_249:
	v_bfe_u32 v2, v3, 16, 1
	v_add3_u32 v2, v3, v2, s96
	global_store_short_d16_hi v[20:21], v2, off offset:96 nt

; template <int EPI>
; __device__ void gemm_phase(const u16* __restrict__ A, const u16* __restrict__ Bt, void* __restrict__ Cv,
;                            int N, int K, int ldc, unsigned char* ldsraw, int G) {
;     ...
;           for (int j = 0; j < 4; ++j) if (nb + j * 16 < N) cp[j * 16] = acc[i][j][r];
;         } else {
;           u16* cp = (u16*)Cv + (size_t)m * ldc + nb;
; #pragma unroll
;           for (int j = 0; j < 4; ++j) {
;             float v = acc[i][j][r];
;             if (EPI == EPI_RELU2) { v = fmaxf(v, 0.f); v = v * v; }
;             if (nb + j * 16 < N) cp[j * 16] = f2bf(v);
.LBB0_254:
	v_bfe_u32 v8, v4, 16, 1
	v_add3_u32 v4, v4, v8, s96
	global_store_short_d16_hi v[2:3], v4, off offset:96 nt

; template <int EPI>
; __device__ void gemm_phase(const u16* __restrict__ A, const u16* __restrict__ Bt, void* __restrict__ Cv,
;                            int N, int K, int ldc, unsigned char* ldsraw, int G) {
;     ...
;           for (int j = 0; j < 4; ++j) if (nb + j * 16 < N) cp[j * 16] = acc[i][j][r];
;         } else {
;           u16* cp = (u16*)Cv + (size_t)m * ldc + nb;
; #pragma unroll
;           for (int j = 0; j < 4; ++j) {
;             float v = acc[i][j][r];
;             if (EPI == EPI_RELU2) { v = fmaxf(v, 0.f); v = v * v; }
;             if (nb + j * 16 < N) cp[j * 16] = f2bf(v);
.LBB0_259:
	v_bfe_u32 v52, v65, 16, 1
	v_add3_u32 v52, v65, v52, s96
	global_store_short_d16_hi v[80:81], v52, off nt
	s_or_b64 exec, exec, s[0:1]
	s_and_saveexec_b64 s[0:1], s[4:5]
	s_cbranch_execz .LBB0_187
.LBB0_260:
	v_bfe_u32 v52, v61, 16, 1
	v_add3_u32 v52, v61, v52, s96
	global_store_short_d16_hi v[80:81], v52, off offset:32 nt
	s_or_b64 exec, exec, s[0:1]
	s_and_saveexec_b64 s[0:1], s[6:7]
	s_cbranch_execz .LBB0_188
.LBB0_261:
	v_bfe_u32 v52, v57, 16, 1
	v_add3_u32 v52, v57, v52, s96
	global_store_short_d16_hi v[80:81], v52, off offset:64 nt
	s_or_b64 exec, exec, s[0:1]
	s_and_saveexec_b64 s[0:1], s[8:9]
	s_cbranch_execnz .LBB0_189
	s_branch .LBB0_190
.LBB0_262:
	v_bfe_u32 v56, v66, 16, 1
	v_add3_u32 v56, v66, v56, s96
	global_store_short_d16_hi v[52:53], v56, off nt
	s_or_b64 exec, exec, s[0:1]
	s_and_saveexec_b64 s[0:1], s[4:5]
	s_cbranch_execz .LBB0_192
.LBB0_263:
	v_bfe_u32 v56, v62, 16, 1
	v_add3_u32 v56, v62, v56, s96
	global_store_short_d16_hi v[52:53], v56, off offset:32 nt
	s_or_b64 exec, exec, s[0:1]
	s_and_saveexec_b64 s[0:1], s[6:7]
	s_cbranch_execz .LBB0_193
.LBB0_264:
	v_bfe_u32 v56, v58, 16, 1
	v_add3_u32 v56, v58, v56, s96
	global_store_short_d16_hi v[52:53], v56, off offset:64 nt
	s_or_b64 exec, exec, s[0:1]
	s_and_saveexec_b64 s[0:1], s[8:9]
	s_cbranch_execnz .LBB0_194
	s_branch .LBB0_195
.LBB0_265:
	v_bfe_u32 v54, v67, 16, 1
	v_add3_u32 v54, v67, v54, s96
	global_store_short_d16_hi v[52:53], v54, off nt
	s_or_b64 exec, exec, s[0:1]
	s_and_saveexec_b64 s[0:1], s[4:5]
	s_cbranch_execz .LBB0_197
.LBB0_266:
	v_bfe_u32 v54, v63, 16, 1
	v_add3_u32 v54, v63, v54, s96
	global_store_short_d16_hi v[52:53], v54, off offset:32 nt
	s_or_b64 exec, exec, s[0:1]
	s_and_saveexec_b64 s[0:1], s[6:7]
	s_cbranch_execz .LBB0_198
.LBB0_267:
	v_bfe_u32 v54, v59, 16, 1
	v_add3_u32 v54, v59, v54, s96
	global_store_short_d16_hi v[52:53], v54, off offset:64 nt
	s_or_b64 exec, exec, s[0:1]
	s_and_saveexec_b64 s[0:1], s[8:9]
	s_cbranch_execnz .LBB0_199
	s_branch .LBB0_200
.LBB0_268:
	v_bfe_u32 v54, v48, 16, 1
	v_add3_u32 v48, v48, v54, s96
	global_store_short_d16_hi v[52:53], v48, off nt
	s_or_b64 exec, exec, s[0:1]
	s_and_saveexec_b64 s[0:1], s[4:5]
	s_cbranch_execz .LBB0_202
.LBB0_269:
	v_bfe_u32 v48, v44, 16, 1
	v_add3_u32 v44, v44, v48, s96
	global_store_short_d16_hi v[52:53], v44, off offset:32 nt
	s_or_b64 exec, exec, s[0:1]
	s_and_saveexec_b64 s[0:1], s[6:7]
	s_cbranch_execz .LBB0_203
.LBB0_270:
	v_bfe_u32 v44, v40, 16, 1
	v_add3_u32 v40, v40, v44, s96
	global_store_short_d16_hi v[52:53], v40, off offset:64 nt
	s_or_b64 exec, exec, s[0:1]
	s_and_saveexec_b64 s[0:1], s[8:9]
	s_cbranch_execnz .LBB0_204
	s_branch .LBB0_205
.LBB0_271:
	v_bfe_u32 v36, v49, 16, 1
	v_add3_u32 v36, v49, v36, s96
	global_store_short_d16_hi v[52:53], v36, off nt
	s_or_b64 exec, exec, s[0:1]
	s_and_saveexec_b64 s[0:1], s[4:5]
	s_cbranch_execz .LBB0_207
.LBB0_272:
	v_bfe_u32 v36, v45, 16, 1
	v_add3_u32 v36, v45, v36, s96
	global_store_short_d16_hi v[52:53], v36, off offset:32 nt
	s_or_b64 exec, exec, s[0:1]
	s_and_saveexec_b64 s[0:1], s[6:7]
	s_cbranch_execz .LBB0_208
.LBB0_273:
	v_bfe_u32 v36, v41, 16, 1
	v_add3_u32 v36, v41, v36, s96
	global_store_short_d16_hi v[52:53], v36, off offset:64 nt
	s_or_b64 exec, exec, s[0:1]
	s_and_saveexec_b64 s[0:1], s[8:9]
	s_cbranch_execnz .LBB0_209
	s_branch .LBB0_210
.LBB0_274:
	v_bfe_u32 v40, v50, 16, 1
	v_add3_u32 v40, v50, v40, s96
	global_store_short_d16_hi v[36:37], v40, off nt
	s_or_b64 exec, exec, s[0:1]
	s_and_saveexec_b64 s[0:1], s[4:5]
	s_cbranch_execz .LBB0_212
.LBB0_275:
	v_bfe_u32 v40, v46, 16, 1
	v_add3_u32 v40, v46, v40, s96
	global_store_short_d16_hi v[36:37], v40, off offset:32 nt
	s_or_b64 exec, exec, s[0:1]
	s_and_saveexec_b64 s[0:1], s[6:7]
	s_cbranch_execz .LBB0_213
.LBB0_276:
	v_bfe_u32 v40, v42, 16, 1
	v_add3_u32 v40, v42, v40, s96
	global_store_short_d16_hi v[36:37], v40, off offset:64 nt
	s_or_b64 exec, exec, s[0:1]
	s_and_saveexec_b64 s[0:1], s[8:9]
	s_cbranch_execnz .LBB0_214
	s_branch .LBB0_215
.LBB0_277:
	v_bfe_u32 v38, v51, 16, 1
	v_add3_u32 v38, v51, v38, s96
	global_store_short_d16_hi v[36:37], v38, off nt
	s_or_b64 exec, exec, s[0:1]
	s_and_saveexec_b64 s[0:1], s[4:5]
	s_cbranch_execz .LBB0_217
.LBB0_278:
	v_bfe_u32 v38, v47, 16, 1
	v_add3_u32 v38, v47, v38, s96
	global_store_short_d16_hi v[36:37], v38, off offset:32 nt
	s_or_b64 exec, exec, s[0:1]
	s_and_saveexec_b64 s[0:1], s[6:7]
	s_cbranch_execz .LBB0_218
.LBB0_279:
	v_bfe_u32 v38, v43, 16, 1
	v_add3_u32 v38, v43, v38, s96
	global_store_short_d16_hi v[36:37], v38, off offset:64 nt
	s_or_b64 exec, exec, s[0:1]
	s_and_saveexec_b64 s[0:1], s[8:9]
	s_cbranch_execnz .LBB0_219
	s_branch .LBB0_220
.LBB0_280:
	v_bfe_u32 v38, v32, 16, 1
	v_add3_u32 v32, v32, v38, s96
	global_store_short_d16_hi v[36:37], v32, off nt
	s_or_b64 exec, exec, s[0:1]
	s_and_saveexec_b64 s[0:1], s[4:5]
	s_cbranch_execz .LBB0_222
.LBB0_281:
	v_bfe_u32 v32, v28, 16, 1
	v_add3_u32 v28, v28, v32, s96
	global_store_short_d16_hi v[36:37], v28, off offset:32 nt
	s_or_b64 exec, exec, s[0:1]
	s_and_saveexec_b64 s[0:1], s[6:7]
	s_cbranch_execz .LBB0_223
; template <int EPI>
; __device__ void gemm_phase(const u16* __restrict__ A, const u16* __restrict__ Bt, void* __restrict__ Cv,
;                            int N, int K, int ldc, unsigned char* ldsraw, int G) {
;     ...
;           for (int j = 0; j < 4; ++j) if (nb + j * 16 < N) cp[j * 16] = acc[i][j][r];
;         } else {
;           u16* cp = (u16*)Cv + (size_t)m * ldc + nb;
; #pragma unroll
;           for (int j = 0; j < 4; ++j) {
;             float v = acc[i][j][r];
;             if (EPI == EPI_RELU2) { v = fmaxf(v, 0.f); v = v * v; }
;             if (nb + j * 16 < N) cp[j * 16] = f2bf(v);
.LBB0_282:
	v_bfe_u32 v28, v24, 16, 1
	v_add3_u32 v24, v24, v28, s96
	global_store_short_d16_hi v[36:37], v24, off offset:64 nt
	s_or_b64 exec, exec, s[0:1]
	s_and_saveexec_b64 s[0:1], s[8:9]
	s_cbranch_execnz .LBB0_224
	s_branch .LBB0_225
.LBB0_283:
	v_bfe_u32 v20, v33, 16, 1
	v_add3_u32 v20, v33, v20, s96
	global_store_short_d16_hi v[36:37], v20, off nt
	s_or_b64 exec, exec, s[0:1]
	s_and_saveexec_b64 s[0:1], s[4:5]
	s_cbranch_execz .LBB0_227
.LBB0_284:
	v_bfe_u32 v20, v29, 16, 1
	v_add3_u32 v20, v29, v20, s96
	global_store_short_d16_hi v[36:37], v20, off offset:32 nt
	s_or_b64 exec, exec, s[0:1]
	s_and_saveexec_b64 s[0:1], s[6:7]
	s_cbranch_execz .LBB0_228
.LBB0_285:
	v_bfe_u32 v20, v25, 16, 1
	v_add3_u32 v20, v25, v20, s96
	global_store_short_d16_hi v[36:37], v20, off offset:64 nt
	s_or_b64 exec, exec, s[0:1]
	s_and_saveexec_b64 s[0:1], s[8:9]
	s_cbranch_execnz .LBB0_229
	s_branch .LBB0_230
.LBB0_286:
	v_bfe_u32 v24, v34, 16, 1
	v_add3_u32 v24, v34, v24, s96
	global_store_short_d16_hi v[20:21], v24, off nt
	s_or_b64 exec, exec, s[0:1]
	s_and_saveexec_b64 s[0:1], s[4:5]
	s_cbranch_execz .LBB0_232
.LBB0_287:
	v_bfe_u32 v24, v30, 16, 1
	v_add3_u32 v24, v30, v24, s96
	global_store_short_d16_hi v[20:21], v24, off offset:32 nt
	s_or_b64 exec, exec, s[0:1]
	s_and_saveexec_b64 s[0:1], s[6:7]
	s_cbranch_execz .LBB0_233
.LBB0_288:
	v_bfe_u32 v24, v26, 16, 1
	v_add3_u32 v24, v26, v24, s96
	global_store_short_d16_hi v[20:21], v24, off offset:64 nt
	s_or_b64 exec, exec, s[0:1]
	s_and_saveexec_b64 s[0:1], s[8:9]
	s_cbranch_execnz .LBB0_234
	s_branch .LBB0_235
.LBB0_289:
	v_bfe_u32 v22, v35, 16, 1
	v_add3_u32 v22, v35, v22, s96
	global_store_short_d16_hi v[20:21], v22, off nt
	s_or_b64 exec, exec, s[0:1]
	s_and_saveexec_b64 s[0:1], s[4:5]
	s_cbranch_execz .LBB0_237
.LBB0_290:
	v_bfe_u32 v22, v31, 16, 1
	v_add3_u32 v22, v31, v22, s96
	global_store_short_d16_hi v[20:21], v22, off offset:32 nt
	s_or_b64 exec, exec, s[0:1]
	s_and_saveexec_b64 s[0:1], s[6:7]
	s_cbranch_execz .LBB0_238
.LBB0_291:
	v_bfe_u32 v22, v27, 16, 1
	v_add3_u32 v22, v27, v22, s96
	global_store_short_d16_hi v[20:21], v22, off offset:64 nt
	s_or_b64 exec, exec, s[0:1]
	s_and_saveexec_b64 s[0:1], s[8:9]
	s_cbranch_execnz .LBB0_239
	s_branch .LBB0_240
.LBB0_292:
	v_bfe_u32 v22, v16, 16, 1
	v_add3_u32 v16, v16, v22, s96
	global_store_short_d16_hi v[20:21], v16, off nt
	s_or_b64 exec, exec, s[0:1]
	s_and_saveexec_b64 s[0:1], s[4:5]
	s_cbranch_execz .LBB0_242
.LBB0_293:
	v_bfe_u32 v16, v12, 16, 1
	v_add3_u32 v12, v12, v16, s96
	global_store_short_d16_hi v[20:21], v12, off offset:32 nt
	s_or_b64 exec, exec, s[0:1]
	s_and_saveexec_b64 s[0:1], s[6:7]
	s_cbranch_execz .LBB0_243
.LBB0_294:
	v_bfe_u32 v12, v8, 16, 1
	v_add3_u32 v8, v8, v12, s96
	global_store_short_d16_hi v[20:21], v8, off offset:64 nt
	s_or_b64 exec, exec, s[0:1]
	s_and_saveexec_b64 s[0:1], s[8:9]
	s_cbranch_execnz .LBB0_244
	s_branch .LBB0_245
.LBB0_295:
	v_bfe_u32 v2, v17, 16, 1
	v_add3_u32 v2, v17, v2, s96
	global_store_short_d16_hi v[20:21], v2, off nt
	s_or_b64 exec, exec, s[0:1]
	s_and_saveexec_b64 s[0:1], s[4:5]
	s_cbranch_execz .LBB0_247
.LBB0_296:
	v_bfe_u32 v2, v13, 16, 1
	v_add3_u32 v2, v13, v2, s96
	global_store_short_d16_hi v[20:21], v2, off offset:32 nt
	s_or_b64 exec, exec, s[0:1]
	s_and_saveexec_b64 s[0:1], s[6:7]
	s_cbranch_execz .LBB0_248
.LBB0_297:
	v_bfe_u32 v2, v9, 16, 1
	v_add3_u32 v2, v9, v2, s96
	global_store_short_d16_hi v[20:21], v2, off offset:64 nt
	s_or_b64 exec, exec, s[0:1]
	s_and_saveexec_b64 s[0:1], s[8:9]
	s_cbranch_execnz .LBB0_249
	s_branch .LBB0_250
.LBB0_298:
	v_bfe_u32 v8, v18, 16, 1
	v_add3_u32 v8, v18, v8, s96
	global_store_short_d16_hi v[2:3], v8, off nt
	s_or_b64 exec, exec, s[0:1]
	s_and_saveexec_b64 s[0:1], s[4:5]
	s_cbranch_execz .LBB0_252
.LBB0_299:
	v_bfe_u32 v8, v14, 16, 1
	v_add3_u32 v8, v14, v8, s96
	global_store_short_d16_hi v[2:3], v8, off offset:32 nt
	s_or_b64 exec, exec, s[0:1]
	s_and_saveexec_b64 s[0:1], s[6:7]
	s_cbranch_execz .LBB0_253
.LBB0_300:
	v_bfe_u32 v8, v10, 16, 1
	v_add3_u32 v8, v10, v8, s96
	global_store_short_d16_hi v[2:3], v8, off offset:64 nt
	s_or_b64 exec, exec, s[0:1]
	s_and_saveexec_b64 s[0:1], s[8:9]
	s_cbranch_execnz .LBB0_254
	s_branch .LBB0_255
.LBB0_301:
	v_bfe_u32 v4, v19, 16, 1
	v_add3_u32 v4, v19, v4, s96
	global_store_short_d16_hi v[2:3], v4, off nt
	s_or_b64 exec, exec, s[0:1]
	s_and_saveexec_b64 s[0:1], s[4:5]
	s_cbranch_execz .LBB0_257
.LBB0_302:
	v_bfe_u32 v4, v15, 16, 1
	v_add3_u32 v4, v15, v4, s96
	global_store_short_d16_hi v[2:3], v4, off offset:32 nt
	s_or_b64 exec, exec, s[0:1]
	s_and_saveexec_b64 s[0:1], s[6:7]
	s_cbranch_execz .LBB0_258
.LBB0_303:
	v_bfe_u32 v4, v11, 16, 1
	v_add3_u32 v4, v11, v4, s96
	global_store_short_d16_hi v[2:3], v4, off offset:64 nt
	s_or_b64 exec, exec, s[0:1]
	s_and_saveexec_b64 s[0:1], s[8:9]
	s_cbranch_execz .LBB0_172
.LBB0_304:
	v_bfe_u32 v4, v5, 16, 1
	v_add3_u32 v4, v5, v4, s96
	global_store_short_d16_hi v[2:3], v4, off offset:96 nt
	s_branch .LBB0_172
